# mla_sample_unit in-loop LDS staging: blocks 1..9 reuse block 0's LDS addresses with immediate offsets (about 120 fewer address VALU per 128-key step on the Ph5 critical path)
# speedup vs baseline: 1.0122x; 1.0013x over previous
.LBB0_901:
	s_andn2_b64 vcc, exec, s[8:9]
	s_waitcnt lgkmcnt(0)
	s_barrier
	s_cbranch_vccnz .LBB0_750
	v_cmp_lt_i32_e32 vcc, s0, v180
	v_mul_u32_u24_e32 v1, 0x150, v184
	s_waitcnt vmcnt(0)
	v_cvt_pk_bf16_f32 v3, v114, v115
	v_cndmask_b32_e32 v2, 0, v172, vcc
	v_add_u32_e32 v2, v2, v180
	v_ashrrev_i32_e32 v2, 6, v2
	v_bfi_b32 v5, -4, v2, v185
	v_cndmask_b32_e32 v4, 0, v173, vcc
	v_add_u32_e32 v4, 0, v4
	v_lshlrev_b32_e32 v8, 3, v5
	v_cvt_pk_bf16_f32 v2, v112, v113
	v_add3_u32 v4, v4, v8, v1
	v_mov_b32_e32 v246, v4
	ds_write_b64 v4, v[2:3] offset:43008
	v_cmp_gt_i32_e64 s[2:3], 32, v5
	v_lshlrev_b32_e32 v4, 1, v184
	s_and_saveexec_b64 s[4:5], s[2:3]
	s_cbranch_execz .LBB0_904
	v_cndmask_b32_e32 v8, 0, v174, vcc
	s_add_i32 s2, 0, 0x15000
	v_add_u32_e32 v8, s2, v8
	v_mul_lo_u32 v5, v5, s47
	v_add3_u32 v5, v8, v5, v4
	v_mov_b32_e32 v247, v5
	ds_write_b16 v5, v2
	ds_write_b16_d16_hi v5, v2 offset:136
	ds_write_b16 v5, v3 offset:272
	ds_write_b16_d16_hi v5, v3 offset:408
.LBB0_904:
	s_or_b64 exec, exec, s[4:5]
	v_cvt_pk_bf16_f32 v8, v116, v117
	v_cvt_pk_bf16_f32 v9, v118, v119
	ds_write_b64 v246, v[8:9] offset:43072
	ds_write_b16 v247, v8 offset:4352
	ds_write_b16_d16_hi v247, v8 offset:4488
	ds_write_b16 v247, v9 offset:4624
	ds_write_b16_d16_hi v247, v9 offset:4760
	v_cvt_pk_bf16_f32 v2, v120, v121
	v_cvt_pk_bf16_f32 v3, v122, v123
	ds_write_b64 v246, v[2:3] offset:43136
	ds_write_b16 v247, v2 offset:8704
	ds_write_b16_d16_hi v247, v2 offset:8840
	ds_write_b16 v247, v3 offset:8976
	ds_write_b16_d16_hi v247, v3 offset:9112
	v_cvt_pk_bf16_f32 v8, v124, v125
	v_cvt_pk_bf16_f32 v9, v126, v127
	ds_write_b64 v246, v[8:9] offset:43200
	ds_write_b16 v247, v8 offset:13056
	ds_write_b16_d16_hi v247, v8 offset:13192
	ds_write_b16 v247, v9 offset:13328
	ds_write_b16_d16_hi v247, v9 offset:13464
	v_cvt_pk_bf16_f32 v2, v128, v129
	v_cvt_pk_bf16_f32 v3, v130, v131
	ds_write_b64 v246, v[2:3] offset:43264
	v_cvt_pk_bf16_f32 v8, v132, v133
	v_cvt_pk_bf16_f32 v9, v134, v135
	ds_write_b64 v246, v[8:9] offset:64512
	ds_write_b16 v247, v8 offset:17408
	ds_write_b16_d16_hi v247, v8 offset:17544
	ds_write_b16 v247, v9 offset:17680
	ds_write_b16_d16_hi v247, v9 offset:17816
	v_cvt_pk_bf16_f32 v2, v136, v137
	v_cvt_pk_bf16_f32 v3, v138, v139
	ds_write_b64 v246, v[2:3] offset:64576
	ds_write_b16 v247, v2 offset:21760
	ds_write_b16_d16_hi v247, v2 offset:21896
	ds_write_b16 v247, v3 offset:22032
	ds_write_b16_d16_hi v247, v3 offset:22168
	v_cvt_pk_bf16_f32 v8, v140, v141
	v_cvt_pk_bf16_f32 v9, v142, v143
	ds_write_b64 v246, v[8:9] offset:64640
	ds_write_b16 v247, v8 offset:26112
	ds_write_b16_d16_hi v247, v8 offset:26248
	ds_write_b16 v247, v9 offset:26384
	ds_write_b16_d16_hi v247, v9 offset:26520
	v_cvt_pk_bf16_f32 v2, v144, v145
	v_cvt_pk_bf16_f32 v3, v146, v147
	ds_write_b64 v246, v[2:3] offset:64704
	ds_write_b16 v247, v2 offset:30464
	ds_write_b16_d16_hi v247, v2 offset:30600
	ds_write_b16 v247, v3 offset:30736
	ds_write_b16_d16_hi v247, v3 offset:30872
	v_cvt_pk_bf16_f32 v8, v148, v149
	v_cvt_pk_bf16_f32 v9, v150, v151
	ds_write_b64 v246, v[8:9] offset:64768
	s_mov_b64 s[2:3], 0
	s_mov_b64 s[4:5], exec
	s_mov_b64 vcc, exec
	s_branch .LBB0_749
